# retA: item index decoded head-fastest (workgroups running together read 2 KB contiguous per row and tensor)
# speedup vs baseline: 1.0015x; 1.0015x over previous
.LBB0_345:
	v_readlane_b32 s0, v255, 1
	s_barrier
	v_mbcnt_lo_u32_b32 v33, -1, 0
	v_mbcnt_hi_u32_b32 v33, -1, v33
	s_cmpk_gt_u32 s2, 0x7ff
	v_add_u32_e32 v0, s0, v33
	v_ashrrev_i32_e32 v32, 5, v0
	v_and_b32_e32 v34, 31, v33
	s_cbranch_scc1 .LBB0_347
	s_lshl_b32 s0, s2, 4
	s_lshl_b32 s1, s2, 4
	s_and_b32 s0, s0, 0x6000
	s_and_b32 s1, s1, 0x1fc0
	s_or_b32 s0, s0, s1
	v_add_u32_e32 v2, s0, v32
	s_movk_i32 s0, 0x3000
	v_mov_b64_e32 v[0:1], s[62:63]
	v_mad_i64_i32 v[0:1], s[0:1], v2, s0, v[0:1]
	s_lshl_b32 s0, s2, 9
	s_and_b32 s0, s0, 0x600
	s_mov_b32 s1, 0
	v_lshl_add_u64 v[0:1], v[0:1], 0, s[0:1]
	v_lshlrev_b32_e32 v2, 4, v34
	v_mov_b32_e32 v3, 0
	v_lshl_add_u64 v[20:21], v[0:1], 0, v[2:3]
	s_mov_b32 s0, 0x30000
	v_add_co_u32_e32 v12, vcc, s0, v20
	s_mov_b32 s0, 0x60000
	s_nop 0
	v_addc_co_u32_e32 v13, vcc, 0, v21, vcc
	v_add_co_u32_e32 v22, vcc, s0, v20
	s_mov_b32 s0, 0x90000
	s_nop 0
	v_addc_co_u32_e32 v23, vcc, 0, v21, vcc
	v_add_co_u32_e32 v36, vcc, s0, v20
	global_load_dwordx4 v[0:3], v[20:21], off
	global_load_dwordx4 v[4:7], v[20:21], off offset:2048
	v_addc_co_u32_e32 v37, vcc, 0, v21, vcc
	global_load_dwordx4 v[16:19], v[12:13], off
	global_load_dwordx4 v[8:11], v[12:13], off offset:2048
	global_load_dwordx4 v[24:27], v[22:23], off
	s_nop 0
	global_load_dwordx4 v[12:15], v[22:23], off offset:2048
	global_load_dwordx4 v[28:31], v[36:37], off
	s_nop 0
	global_load_dwordx4 v[20:23], v[36:37], off offset:2048
	s_branch .LBB0_348

.LBB0_350:
	s_and_b32 s4, s36, 3
	s_waitcnt vmcnt(7)
	ds_write_b128 v46, v[0:3]
	s_waitcnt vmcnt(6)
	ds_write_b128 v46, v[4:7] offset:33792
	s_waitcnt vmcnt(5)
	ds_write_b128 v46, v[16:19] offset:8448
	s_waitcnt vmcnt(4)
	ds_write_b128 v46, v[8:11] offset:42240
	s_waitcnt vmcnt(3)
	ds_write_b128 v46, v[24:27] offset:16896
	s_waitcnt vmcnt(2)
	ds_write_b128 v46, v[12:15] offset:50688
	s_waitcnt vmcnt(1)
	ds_write_b128 v46, v[28:31] offset:25344
	s_waitcnt vmcnt(0)
	ds_write_b128 v46, v[20:23] offset:59136
	v_cvt_f32_ubyte0_e32 v26, s4
	v_sub_f32_e32 v26, 0xc0a00000, v26
	v_cmp_gt_f32_e32 vcc, s0, v26
	s_and_b64 s[4:5], vcc, exec
	s_cselect_b32 s6, 0xffffffc0, 0
	s_add_i32 s10, s36, s33
	v_cndmask_b32_e32 v27, 0, v50, vcc
	s_cmpk_lt_i32 s10, 0x800
	v_add_f32_e32 v26, v26, v27
	s_cselect_b64 s[4:5], -1, 0
	v_exp_f32_e32 v26, v26
	s_and_b64 vcc, s[4:5], exec
	s_waitcnt lgkmcnt(0)
	s_barrier
	ds_read_b128 v[0:3], v47
	ds_read_b128 v[4:7], v47 offset:64
	ds_read_b128 v[8:11], v48 offset:33792
	ds_read_b128 v[12:15], v48 offset:33856
	ds_read_b128 v[16:19], v49 offset:33792
	ds_read_b128 v[20:23], v49 offset:33856
	ds_read_b128 v[52:55], v47 offset:128
	ds_read_b128 v[56:59], v47 offset:192
	ds_read_b128 v[60:63], v48 offset:33920
	ds_read_b128 v[64:67], v48 offset:33984
	ds_read_b128 v[68:71], v49 offset:33920
	ds_read_b128 v[72:75], v49 offset:33984
	ds_read_b128 v[76:79], v47 offset:256
	ds_read_b128 v[80:83], v47 offset:320
	ds_read_b128 v[84:87], v48 offset:34048
	ds_read_b128 v[88:91], v48 offset:34112
	ds_read_b128 v[92:95], v49 offset:34048
	ds_read_b128 v[96:99], v49 offset:34112
	ds_read_b128 v[100:103], v47 offset:384
	ds_read_b128 v[104:107], v47 offset:448
	ds_read_b128 v[108:111], v48 offset:34176
	ds_read_b128 v[112:115], v48 offset:34240
	ds_read_b128 v[116:119], v49 offset:34176
	ds_read_b128 v[120:123], v49 offset:34240
	s_cselect_b32 s5, s10, s36
	s_waitcnt lgkmcnt(14)
	v_mfma_f32_16x16x32_bf16 v[8:11], v[8:11], v[0:3], 0
	s_ashr_i32 s4, s5, 9
	s_ashr_i32 s37, s36, 31
	s_lshl_b32 s11, s5, 4
	v_mfma_f32_16x16x32_bf16 v[0:3], v[16:19], v[0:3], 0
	s_lshl_b32 s12, s5, 9
	s_ashr_i32 s5, s4, 31
	v_ldexp_f32 v26, v26, s6
	s_and_b32 s100, s36, 3
	s_lshl_b32 s100, s100, 7
	s_bfe_u32 s101, s36, 0x70002
	s_or_b32 s100, s100, s101
	s_and_b32 s101, s36, 0x600
	s_or_b32 s100, s100, s101
	s_mov_b32 s101, 0
	s_lshl_b64 s[6:7], s[100:101], 13
	s_mov_b32 s36, s10
	s_and_b32 s10, s11, 0x1fc0
	s_lshl_b64 s[4:5], s[4:5], 13
	s_or_b32 s4, s4, s10
	v_mov_b64_e32 v[24:25], s[62:63]
	v_mfma_f32_16x16x32_bf16 v[128:131], v[20:23], v[4:7], v[0:3]
	s_and_b32 s24, s12, 0x600
	v_sub_f32_e32 v16, 1.0, v26
	v_log_f32_e32 v134, v16
	v_lshl_add_u64 v[0:1], s[4:5], 0, v[32:33]
	v_mad_u64_u32 v[2:3], s[4:5], v0, s1, v[24:25]
	v_mad_i32_i24 v3, v1, s1, v3
	v_lshl_add_u64 v[0:1], v[2:3], 0, s[24:25]
	v_mfma_f32_16x16x32_bf16 v[124:127], v[12:15], v[4:7], v[8:11]
	v_mul_f32_e32 v135, v134, v39
	v_mul_f32_e32 v136, v134, v40
	v_mul_f32_e32 v137, v134, v41
	v_lshl_add_u64 v[8:9], v[0:1], 0, v[34:35]
	v_add_co_u32_e64 v10, s[4:5], s27, v8
	global_load_dwordx4 v[0:3], v[8:9], off
	global_load_dwordx4 v[4:7], v[8:9], off offset:2048
	v_addc_co_u32_e64 v11, s[4:5], 0, v9, s[4:5]
	v_add_co_u32_e64 v12, s[4:5], s38, v8
	v_mfma_f32_16x16x32_bf16 v[60:63], v[60:63], v[52:55], v[124:127]
	s_nop 0
	v_addc_co_u32_e64 v13, s[4:5], 0, v9, s[4:5]
	v_add_co_u32_e64 v20, s[4:5], s39, v8
	s_waitcnt lgkmcnt(13)
	v_mfma_f32_16x16x32_bf16 v[52:55], v[68:71], v[52:55], v[128:131]
	v_addc_co_u32_e64 v21, s[4:5], 0, v9, s[4:5]
	global_load_dwordx4 v[16:19], v[10:11], off
	s_nop 0
	global_load_dwordx4 v[8:11], v[10:11], off offset:2048
	s_nop 0
	global_load_dwordx4 v[24:27], v[12:13], off
	s_nop 0
	global_load_dwordx4 v[12:15], v[12:13], off offset:2048
	s_nop 0
	global_load_dwordx4 v[28:31], v[20:21], off
	s_nop 0
	global_load_dwordx4 v[20:23], v[20:21], off offset:2048
	v_mfma_f32_16x16x32_bf16 v[60:63], v[64:67], v[56:59], v[60:63]
	v_mul_f32_e32 v138, v134, v42
	v_lshl_add_u64 v[132:133], v[36:37], 0, s[6:7]
	v_mul_f32_e32 v139, v134, v38
	s_waitcnt lgkmcnt(12)
	v_mfma_f32_16x16x32_bf16 v[52:55], v[72:75], v[56:59], v[52:55]
	v_mul_f32_e32 v140, v134, v43
	v_mul_f32_e32 v141, v134, v44
	v_mul_f32_e32 v142, v134, v45
	s_waitcnt lgkmcnt(9)
	v_mfma_f32_16x16x32_bf16 v[56:59], v[84:87], v[76:79], v[60:63]
	v_cmp_gt_f32_e64 s[4:5], s0, v135
	v_cmp_gt_f32_e64 s[6:7], s0, v136
	v_cmp_gt_f32_e64 s[10:11], s0, v137
	s_waitcnt lgkmcnt(7)
	v_mfma_f32_16x16x32_bf16 v[52:55], v[92:95], v[76:79], v[52:55]
	v_cmp_gt_f32_e64 s[12:13], s0, v138
	v_cndmask_b32_e64 v135, 0, v50, s[4:5]
	v_cndmask_b32_e64 v136, 0, v50, s[6:7]
	v_mfma_f32_16x16x32_bf16 v[56:59], v[88:91], v[80:83], v[56:59]
	v_cndmask_b32_e64 v137, 0, v50, s[10:11]
	v_cndmask_b32_e64 v138, 0, v50, s[12:13]
	v_cmp_gt_f32_e64 s[14:15], s0, v139
	s_waitcnt lgkmcnt(6)
	v_mfma_f32_16x16x32_bf16 v[52:55], v[96:99], v[80:83], v[52:55]
	v_cmp_gt_f32_e64 s[16:17], s0, v140
	v_cmp_gt_f32_e64 s[18:19], s0, v141
	v_cmp_gt_f32_e64 s[20:21], s0, v142
	s_waitcnt lgkmcnt(3)
	v_mfma_f32_16x16x32_bf16 v[56:59], v[108:111], v[100:103], v[56:59]
	v_cndmask_b32_e64 v139, 0, v50, s[14:15]
	v_cndmask_b32_e64 v140, 0, v50, s[16:17]
	v_cndmask_b32_e64 v124, 0, v50, s[18:19]
	s_waitcnt lgkmcnt(1)
	v_mfma_f32_16x16x32_bf16 v[52:55], v[116:119], v[100:103], v[52:55]
	v_cndmask_b32_e64 v125, 0, v50, s[20:21]
	v_fmac_f32_e32 v135, v134, v39
	v_fmac_f32_e32 v136, v134, v40
	v_fmac_f32_e32 v137, v134, v41
	v_fmac_f32_e32 v138, v134, v42
	v_fmac_f32_e32 v139, v134, v38
	v_fmac_f32_e32 v140, v134, v43
	v_fmac_f32_e32 v124, v134, v44
	v_fmac_f32_e32 v125, v134, v45
	v_exp_f32_e32 v60, v135
	v_exp_f32_e32 v61, v136
	v_exp_f32_e32 v62, v137
	v_exp_f32_e32 v63, v138
	v_exp_f32_e32 v72, v139
	v_exp_f32_e32 v73, v140
	v_exp_f32_e32 v74, v124
	v_exp_f32_e32 v75, v125
	v_mfma_f32_16x16x32_bf16 v[56:59], v[112:115], v[104:107], v[56:59]
	v_cndmask_b32_e64 v68, 0, v51, s[4:5]
	v_cndmask_b32_e64 v69, 0, v51, s[6:7]
	v_cndmask_b32_e64 v64, 0, v51, s[10:11]
	s_waitcnt lgkmcnt(0)
	v_mfma_f32_16x16x32_bf16 v[52:55], v[120:123], v[104:107], v[52:55]
	v_cndmask_b32_e64 v65, 0, v51, s[12:13]
	v_cndmask_b32_e64 v66, 0, v51, s[14:15]
	v_cndmask_b32_e64 v67, 0, v51, s[16:17]
	v_cndmask_b32_e64 v70, 0, v51, s[18:19]
	v_cndmask_b32_e64 v71, 0, v51, s[20:21]
	v_ldexp_f32 v60, v60, v68
	v_ldexp_f32 v61, v61, v69
	v_ldexp_f32 v62, v62, v64
	v_ldexp_f32 v63, v63, v65
	v_ldexp_f32 v64, v72, v66
	v_ldexp_f32 v65, v73, v67
	v_ldexp_f32 v66, v74, v70
	v_ldexp_f32 v67, v75, v71
	v_pk_mul_f32 v[56:57], v[60:61], v[56:57]
	v_pk_mul_f32 v[58:59], v[62:63], v[58:59]
	v_pk_mul_f32 v[52:53], v[64:65], v[52:53]
	v_pk_mul_f32 v[54:55], v[66:67], v[54:55]
	v_cvt_pk_bf16_f32 v56, v56, v57
	v_cvt_pk_bf16_f32 v57, v58, v59
	v_cvt_pk_bf16_f32 v52, v52, v53
	v_cvt_pk_bf16_f32 v53, v54, v55
	global_store_dwordx2 v[132:133], v[56:57], off
	global_store_dwordx2 v[132:133], v[52:53], off offset:32
	s_barrier
	s_cbranch_vccnz .LBB0_350
